# baseline (speedup 1.0000x reference)
; __device__ __forceinline__ u32x2 pack4(f32x4 v) { u32x2 r; r.x = cvt_pk_bf16(v[0], v[1]); r.y = cvt_pk_bf16(v[2], v[3]); return r; }
;     __device__ __forceinline__ void operator()(AccRef acc, const pg8::Unit& u, int wr, int wc, int fr, int fq) const {
;     ...
;                     const f32x4 c0 = bb[bj] + w0[bj] * s2 + w1[bj] * s3 + w2[bj] * h0;
;                     const f32x4 c1 = bb[bj] + w0[bj] * s3 + w1[bj] * h0 + w2[bj] * h1;
;                     const f32x4 c2 = bb[bj] + w0[bj] * h0 + w1[bj] * h1 + w2[bj] * h2;
;                     const f32x4 c3 = bb[bj] + w0[bj] * h1 + w1[bj] * h2 + w2[bj] * h3;
;                     if (bj == 0) { cv[0] = c0; cv[1] = c1; cv[2] = c2; cv[3] = c3; } else { cg[0] = c0; cg[1] = c1; cg[2] = c2; cg[3] = c3; }
;                     if (has_next && fr == 15) {
;                         const size_t o1 = ((size_t)(1 * NSLAB + slab + 1) * 2) * NUP;
;                         *(u32x2*)((bf16_t*)BND + o1 + fc) = pack4(w0[bj] * h2 + w1[bj] * h3); *(u32x2*)((bf16_t*)BND + o1 + NUP + fc) = pack4(w0[bj] * h3);
.LBB0_757:
	s_lshl_b32 s3, s4, 7
	v_mov_b32_e32 v246, v3
	v_mov_b32_e32 v68, v243
	s_or_b32 s3, s3, s58
	s_lshl_b32 s44, s2, 2
	v_lshl_add_u32 v218, v68, 3, s3
	v_ashrrev_i32_e32 v219, 31, v218
	v_add_u32_e32 v220, 0x1580, v218
	v_lshlrev_b64 v[80:81], 2, v[218:219]
	v_ashrrev_i32_e32 v221, 31, v220
	v_lshl_add_u64 v[68:69], s[14:15], 0, v[80:81]
	v_lshl_add_u64 v[72:73], s[18:19], 0, v[80:81]
	v_lshl_add_u64 v[82:83], s[20:21], 0, v[80:81]
	v_lshl_add_u64 v[84:85], s[16:17], 0, v[80:81]
	v_lshlrev_b64 v[96:97], 2, v[220:221]
	global_load_dwordx4 v[76:79], v[68:69], off offset:16
	global_load_dwordx4 v[168:171], v[68:69], off
	s_nop 0
	global_load_dwordx4 v[68:71], v[72:73], off offset:16
	global_load_dwordx4 v[172:175], v[72:73], off
	s_nop 0
	global_load_dwordx4 v[72:75], v[82:83], off offset:16
	global_load_dwordx4 v[164:167], v[82:83], off
	s_nop 0
	global_load_dwordx4 v[80:83], v[84:85], off offset:16
	global_load_dwordx4 v[176:179], v[84:85], off
	v_lshl_add_u64 v[84:85], s[14:15], 0, v[96:97]
	global_load_dwordx4 v[88:91], v[84:85], off offset:16
	global_load_dwordx4 v[180:183], v[84:85], off
	v_lshl_add_u64 v[84:85], s[18:19], 0, v[96:97]
	v_lshl_add_u64 v[98:99], s[20:21], 0, v[96:97]
	v_lshl_add_u64 v[192:193], s[16:17], 0, v[96:97]
	global_load_dwordx4 v[92:95], v[84:85], off offset:16
	global_load_dwordx4 v[184:187], v[84:85], off
	s_nop 0
	global_load_dwordx4 v[84:87], v[98:99], off offset:16
	global_load_dwordx4 v[188:191], v[98:99], off
	s_nop 0
	global_load_dwordx4 v[96:99], v[192:193], off offset:16
	s_nop 0
	global_load_dwordx4 v[192:195], v[192:193], off
	s_add_i32 s44, s44, s50
	s_and_b32 s27, s44, 31
	s_cmp_lg_u32 s27, 31
	v_cmp_eq_u32_e64 s[6:7], 15, v246
	s_cselect_b64 s[2:3], -1, 0
	s_and_b64 s[40:41], s[2:3], s[6:7]
	s_add_i32 s2, s44, 0x81
	s_mul_hi_i32 s39, s2, 0x5600
	s_mul_i32 s38, s2, 0x5600
	v_mov_b32_dpp v228, v144 row_shr:1 row_mask:0xf bank_mask:0xf bound_ctrl:1
	v_mov_b32_dpp v229, v145 row_shr:1 row_mask:0xf bank_mask:0xf bound_ctrl:1
	v_mov_b32_dpp v226, v146 row_shr:1 row_mask:0xf bank_mask:0xf bound_ctrl:1
	v_mov_b32_dpp v227, v147 row_shr:1 row_mask:0xf bank_mask:0xf bound_ctrl:1
	v_mov_b32_dpp v234, v132 row_shr:1 row_mask:0xf bank_mask:0xf bound_ctrl:1
	v_mov_b32_dpp v236, v133 row_shr:1 row_mask:0xf bank_mask:0xf bound_ctrl:1
	v_mov_b32_dpp v235, v134 row_shr:1 row_mask:0xf bank_mask:0xf bound_ctrl:1
	v_mov_b32_dpp v237, v135 row_shr:1 row_mask:0xf bank_mask:0xf bound_ctrl:1
	s_and_saveexec_b64 s[2:3], s[40:41]
	s_cbranch_execz .LBB0_759
	s_lshl_b64 s[4:5], s[38:39], 1
	s_waitcnt vmcnt(0)
	v_mul_f32_e32 v200, v146, v174
	v_mul_f32_e32 v201, v147, v175
	v_mul_f32_e32 v222, v144, v172
	v_mul_f32_e32 v223, v145, v173
	s_add_u32 s4, s56, s4
	v_fma_f32 v200, v134, v170, v200
	v_fma_f32 v201, v135, v171, v201
	v_fma_f32 v222, v132, v168, v222
	v_fma_f32 v223, v133, v169, v223
	s_addc_u32 s5, s57, s5
	v_cvt_pkrtz_f16_f32 v222, v222, v223
	v_cvt_pkrtz_f16_f32 v223, v200, v201
	v_lshl_add_u64 v[200:201], v[218:219], 1, s[4:5]
	flat_store_dwordx2 v[200:201], v[222:223]
	v_mul_f32_e32 v222, v146, v170
	v_mul_f32_e32 v223, v147, v171
	v_mul_f32_e32 v224, v144, v168
	v_mul_f32_e32 v225, v145, v169
	v_add_co_u32_e32 v200, vcc, 0x5000, v200
	v_cvt_pkrtz_f16_f32 v224, v224, v225
	v_cvt_pkrtz_f16_f32 v225, v222, v223
	v_addc_co_u32_e32 v201, vcc, 0, v201, vcc
	flat_store_dwordx2 v[200:201], v[224:225] offset:1536
.LBB0_759:
	s_or_b64 exec, exec, s[2:3]
	v_mov_b32_dpp v224, v136 row_shr:1 row_mask:0xf bank_mask:0xf bound_ctrl:1
	v_mov_b32_dpp v225, v137 row_shr:1 row_mask:0xf bank_mask:0xf bound_ctrl:1
	v_mov_b32_dpp v222, v138 row_shr:1 row_mask:0xf bank_mask:0xf bound_ctrl:1
	v_mov_b32_dpp v223, v139 row_shr:1 row_mask:0xf bank_mask:0xf bound_ctrl:1
	v_mov_b32_dpp v230, v140 row_shr:1 row_mask:0xf bank_mask:0xf bound_ctrl:1
	v_mov_b32_dpp v232, v141 row_shr:1 row_mask:0xf bank_mask:0xf bound_ctrl:1
	v_mov_b32_dpp v231, v142 row_shr:1 row_mask:0xf bank_mask:0xf bound_ctrl:1
	v_mov_b32_dpp v233, v143 row_shr:1 row_mask:0xf bank_mask:0xf bound_ctrl:1
	s_and_saveexec_b64 s[2:3], s[40:41]
	s_cbranch_execz .LBB0_761
	s_lshl_b64 s[4:5], s[38:39], 1
	s_waitcnt vmcnt(0)
	v_mul_f32_e32 v200, v138, v186
	v_mul_f32_e32 v201, v139, v187
	v_mul_f32_e32 v238, v136, v184
	v_mul_f32_e32 v239, v137, v185
	s_add_u32 s4, s56, s4
	v_fma_f32 v200, v142, v182, v200
	v_fma_f32 v201, v143, v183, v201
	v_fma_f32 v238, v140, v180, v238
	v_fma_f32 v239, v141, v181, v239
	s_addc_u32 s5, s57, s5
	v_cvt_pkrtz_f16_f32 v238, v238, v239
	v_cvt_pkrtz_f16_f32 v239, v200, v201
	v_lshl_add_u64 v[200:201], v[220:221], 1, s[4:5]
	flat_store_dwordx2 v[200:201], v[238:239]
	v_mul_f32_e32 v238, v138, v182
	v_mul_f32_e32 v239, v139, v183
	v_mul_f32_e32 v248, v136, v180
	v_mul_f32_e32 v249, v137, v181
	v_add_co_u32_e32 v200, vcc, 0x5000, v200
	v_cvt_pkrtz_f16_f32 v248, v248, v249
	v_cvt_pkrtz_f16_f32 v249, v238, v239
	v_addc_co_u32_e32 v201, vcc, 0, v201, vcc
	flat_store_dwordx2 v[200:201], v[248:249] offset:1536
.LBB0_761:
	s_or_b64 exec, exec, s[2:3]
	v_cmp_eq_u32_e64 s[2:3], 0, v246
	s_cmp_lg_u32 s27, 0
	s_cselect_b64 s[36:37], -1, 0
	v_mov_b32_e32 v201, v232
	v_mov_b32_e32 v200, v230
	s_waitcnt vmcnt(0)
	v_fma_f32 v200, v180, v200, v192
	v_fma_f32 v201, v181, v201, v193
	v_mov_b32_e32 v232, v231
	v_fma_f32 v200, v184, v224, v200
	v_fma_f32 v201, v185, v225, v201
	v_fma_f32 v230, v182, v232, v194
	v_fma_f32 v231, v183, v233, v195
	v_fma_f32 v232, v156, v188, v200
	v_fma_f32 v233, v157, v189, v201
	v_mov_b32_e32 v201, v236
	v_mov_b32_e32 v200, v234
	v_mov_b32_e32 v236, v235
	v_fma_f32 v234, v170, v236, v178
	v_fma_f32 v235, v171, v237, v179
	v_fma_f32 v200, v168, v200, v176
	v_fma_f32 v201, v169, v201, v177
	v_fma_f32 v230, v186, v222, v230
	v_fma_f32 v231, v187, v223, v231
	v_fma_f32 v200, v172, v228, v200
	v_fma_f32 v201, v173, v229, v201
	v_fma_f32 v234, v174, v226, v234
	v_fma_f32 v235, v175, v227, v235
	v_fma_f32 v230, v158, v190, v230
	v_fma_f32 v231, v159, v191, v231
	v_cmp_ne_u32_e64 s[4:5], 0, v246
	v_fma_f32 v234, v162, v166, v234
	v_fma_f32 v235, v163, v167, v235
	v_fma_f32 v236, v160, v164, v200
	v_fma_f32 v237, v161, v165, v201
	s_and_b64 s[36:37], s[2:3], s[36:37]
	s_mul_hi_i32 s27, s44, 0xac00
	s_mul_i32 s29, s44, 0xac00
	s_and_saveexec_b64 s[42:43], s[36:37]
	s_xor_b64 s[42:43], exec, s[42:43]
	s_cbranch_execz .LBB0_763
	s_add_u32 s64, s56, s29
	s_addc_u32 s65, s57, s27
	v_cvt_pkrtz_f16_f32 v200, v236, v237
	v_cvt_pkrtz_f16_f32 v201, v234, v235
	v_lshl_add_u64 v[234:235], v[218:219], 1, s[64:65]
	flat_store_dwordx2 v[234:235], v[200:201]
	v_cvt_pkrtz_f16_f32 v200, v232, v233
	v_cvt_pkrtz_f16_f32 v201, v230, v231
	v_lshl_add_u64 v[230:231], v[220:221], 1, s[64:65]
	flat_store_dwordx2 v[230:231], v[200:201]

;     __device__ __forceinline__ void operator()(AccRef acc, const pg8::Unit& u, int wr, int wc, int fr, int fq) const {
;     ...
;                     const f32x4 c1 = bb[bj] + w0[bj] * s3 + w1[bj] * h0 + w2[bj] * h1;
.LBB0_765:
	s_or_b64 exec, exec, s[42:43]
	v_fma_f32 v200, v182, v222, v194
	v_fma_f32 v201, v183, v223, v195
	v_fma_f32 v222, v180, v224, v192
	v_fma_f32 v223, v181, v225, v193
	v_fma_f32 v200, v158, v186, v200
	v_fma_f32 v201, v159, v187, v201
	v_fma_f32 v224, v156, v184, v222
	v_fma_f32 v225, v157, v185, v223
	v_fma_f32 v222, v154, v190, v200
	v_fma_f32 v223, v155, v191, v201
	v_fma_f32 v230, v152, v188, v224
	v_fma_f32 v231, v153, v189, v225
	v_fma_f32 v200, v170, v226, v178
	v_fma_f32 v201, v171, v227, v179
	v_fma_f32 v224, v168, v228, v176
	v_fma_f32 v225, v169, v229, v177
	v_fma_f32 v200, v162, v174, v200
	v_fma_f32 v201, v163, v175, v201
	v_fma_f32 v226, v160, v172, v224
	v_fma_f32 v227, v161, v173, v225
	v_fma_f32 v224, v150, v166, v200
	v_fma_f32 v225, v151, v167, v201
	v_fma_f32 v226, v148, v164, v226
	v_fma_f32 v227, v149, v165, v227
	s_and_saveexec_b64 s[42:43], s[36:37]
	s_xor_b64 s[42:43], exec, s[42:43]
	s_cbranch_execz .LBB0_767
	s_add_u32 s45, s56, s29
	s_addc_u32 s63, s57, s27
	s_add_u32 s64, s45, 0x5600
	s_addc_u32 s65, s63, 0
	v_cvt_pkrtz_f16_f32 v200, v226, v227
	v_cvt_pkrtz_f16_f32 v201, v224, v225
	v_lshl_add_u64 v[224:225], v[218:219], 1, s[64:65]
	flat_store_dwordx2 v[224:225], v[200:201]
	v_cvt_pkrtz_f16_f32 v200, v230, v231
	v_cvt_pkrtz_f16_f32 v201, v222, v223
	v_lshl_add_u64 v[222:223], v[220:221], 1, s[64:65]
	flat_store_dwordx2 v[222:223], v[200:201]

; __device__ __forceinline__ u32x2 pack4(f32x4 v) { u32x2 r; r.x = cvt_pk_bf16(v[0], v[1]); r.y = cvt_pk_bf16(v[2], v[3]); return r; }
; __device__ __forceinline__ float sigmoidf_(float x) { return __builtin_amdgcn_rcpf(1.0f + __expf(-x)); }
;     __device__ __forceinline__ void operator()(AccRef acc, const pg8::Unit& u, int wr, int wc, int fr, int fq) const {
;     ...
;                     const f32x4 c2 = bb[bj] + w0[bj] * h0 + w1[bj] * h1 + w2[bj] * h2;
;                     const f32x4 c3 = bb[bj] + w0[bj] * h1 + w1[bj] * h2 + w2[bj] * h3;
;                     if (bj == 0) { cv[0] = c0; cv[1] = c1; cv[2] = c2; cv[3] = c3; } else { cg[0] = c0; cg[1] = c1; cg[2] = c2; cg[3] = c3; }
;                     if (has_next && fr == 15) {
;                         const size_t o1 = ((size_t)(1 * NSLAB + slab + 1) * 2) * NUP;
;                         *(u32x2*)((bf16_t*)BND + o1 + fc) = pack4(w0[bj] * h2 + w1[bj] * h3); *(u32x2*)((bf16_t*)BND + o1 + NUP + fc) = pack4(w0[bj] * h3);
;                     }
;                 }
; #pragma unroll
;                 for (int m = 0; m < 4; ++m) {
;                     if (m < 2 && fr == 0 && !bstart) {
;                         const size_t o0 = ((size_t)(0 * NSLAB + slab) * 2 + m) * NUP;
;                         *(u32x2*)((bf16_t*)BND + o0 + fv) = pack4(cv[m]); *(u32x2*)((bf16_t*)BND + o0 + fg) = pack4(cg[m]);
;                     } else {
;                         f32x4 a;
; #pragma unroll
;                         for (int j = 0; j < 4; ++j) a[j] = cv[m][j] * cg[m][j] * sigmoidf_(cg[m][j]);
;                         *(u32x2*)(ACT + (size_t)(slab * 64 + 4 * fr + m) * DFF + fv) = pack4(a);
.LBB0_769:
	s_or_b64 exec, exec, s[42:43]
	v_fma_f32 v200, v154, v182, v194
	v_fma_f32 v201, v155, v183, v195
	v_fma_f32 v222, v152, v180, v192
	v_fma_f32 v223, v153, v181, v193
	v_fma_f32 v200, v142, v186, v200
	v_fma_f32 v201, v143, v187, v201
	v_fma_f32 v222, v140, v184, v222
	v_fma_f32 v223, v141, v185, v223
	v_fma_f32 v138, v138, v190, v200
	v_fma_f32 v139, v139, v191, v201
	v_fma_f32 v200, v136, v188, v222
	v_fma_f32 v201, v137, v189, v223
	v_fma_f32 v136, v158, v182, v194
	v_fma_f32 v137, v159, v183, v195
	v_fma_f32 v156, v156, v180, v192
	v_fma_f32 v157, v157, v181, v193
	v_fma_f32 v136, v154, v186, v136
	v_fma_f32 v137, v155, v187, v137
	v_fma_f32 v152, v152, v184, v156
	v_fma_f32 v153, v153, v185, v157
	v_fma_f32 v136, v142, v190, v136
	v_fma_f32 v137, v143, v191, v137
	v_fma_f32 v142, v150, v170, v178
	v_fma_f32 v143, v151, v171, v179
	v_fma_f32 v140, v140, v188, v152
	v_fma_f32 v141, v141, v189, v153
	v_fma_f32 v142, v134, v174, v142
	v_fma_f32 v143, v135, v175, v143
	v_fma_f32 v152, v148, v168, v176
	v_fma_f32 v153, v149, v169, v177
	v_fma_f32 v142, v146, v166, v142
	v_fma_f32 v143, v147, v167, v143
	v_fma_f32 v146, v162, v170, v178
	v_fma_f32 v147, v163, v171, v179
	v_fma_f32 v152, v132, v172, v152
	v_fma_f32 v153, v133, v173, v153
	v_fma_f32 v146, v150, v174, v146
	v_fma_f32 v147, v151, v175, v147
	v_mul_f32_e32 v150, 0xbfb8aa3b, v140
	v_exp_f32_e32 v150, v150
	v_fma_f32 v134, v134, v166, v146
	v_fma_f32 v135, v135, v167, v147
	v_mul_f32_e32 v147, 0xbfb8aa3b, v141
	v_exp_f32_e32 v147, v147
	v_add_f32_e32 v146, 1.0, v150
	v_fma_f32 v144, v144, v164, v152
	v_fma_f32 v145, v145, v165, v153
	v_fma_f32 v152, v160, v168, v176
	v_fma_f32 v153, v161, v169, v177
	v_rcp_f32_e32 v146, v146
	v_fma_f32 v148, v148, v172, v152
	v_fma_f32 v149, v149, v173, v153
	v_mul_f32_e32 v134, v134, v136
	v_fma_f32 v132, v132, v164, v148
	v_fma_f32 v133, v133, v165, v149
	v_mul_f32_e32 v144, v144, v200
	v_mul_f32_e32 v132, v132, v140
	v_mul_f32_e32 v133, v133, v141
	v_add_f32_e32 v140, 1.0, v147
	v_mul_f32_e32 v141, 0xbfb8aa3b, v136
	v_mul_f32_e32 v132, v132, v146
	v_rcp_f32_e32 v140, v140
	v_exp_f32_e32 v141, v141
	v_mul_f32_e32 v146, 0xbfb8aa3b, v137
	v_exp_f32_e32 v146, v146
	v_mul_f32_e32 v133, v133, v140
	v_add_f32_e32 v140, 1.0, v141
	v_rcp_f32_e32 v140, v140
	v_add_f32_e32 v141, 1.0, v146
	v_rcp_f32_e32 v141, v141
	v_mul_f32_e32 v136, v134, v140
	v_mul_f32_e32 v134, v135, v137
	v_mul_f32_e32 v135, v134, v141
	v_cvt_pkrtz_f16_f32 v135, v136, v135
	v_mul_f32_e32 v136, 0xbfb8aa3b, v200
	v_exp_f32_e32 v146, v136
	v_cvt_pkrtz_f16_f32 v134, v132, v133
	v_or_b32_e32 v132, 2, v246
	v_mov_b64_e32 v[140:141], s[22:23]
	v_mad_i64_i32 v[132:133], s[42:43], v132, s33, v[140:141]
	v_lshlrev_b64 v[136:137], 1, v[218:219]
	v_lshl_add_u64 v[132:133], v[132:133], 0, v[136:137]
	flat_store_dwordx2 v[132:133], v[134:135]
	v_add_f32_e32 v134, 1.0, v146
	v_mul_f32_e32 v135, 0xbfb8aa3b, v201
	v_rcp_f32_e32 v134, v134
	v_exp_f32_e32 v135, v135
	v_mul_f32_e32 v146, 0xbfb8aa3b, v139
	v_exp_f32_e32 v146, v146
	v_mul_f32_e32 v134, v144, v134
	v_mul_f32_e32 v144, v145, v201
	v_add_f32_e32 v135, 1.0, v135
	v_mul_f32_e32 v145, 0xbfb8aa3b, v138
	v_rcp_f32_e32 v135, v135
	v_exp_f32_e32 v145, v145
	v_mul_f32_e32 v138, v142, v138
	v_mul_f32_e32 v135, v144, v135
	v_add_f32_e32 v144, 1.0, v145
	v_rcp_f32_e32 v144, v144
	v_add_f32_e32 v145, 1.0, v146
	v_rcp_f32_e32 v145, v145
	v_mul_f32_e32 v142, v138, v144
	v_mul_f32_e32 v138, v143, v139
	v_mul_f32_e32 v139, v138, v145
	v_cvt_pkrtz_f16_f32 v138, v134, v135
	v_or_b32_e32 v134, 3, v246
	v_mad_i64_i32 v[134:135], s[42:43], v134, s33, v[140:141]
	v_cvt_pkrtz_f16_f32 v139, v142, v139
	v_lshl_add_u64 v[134:135], v[134:135], 0, v[136:137]
	flat_store_dwordx2 v[134:135], v[138:139]
	s_add_i32 s65, s44, 2
	s_and_b32 s63, s65, 31
	s_cmp_lg_u32 s63, 31
	s_cselect_b64 s[42:43], -1, 0
	s_and_b64 s[42:43], s[42:43], s[6:7]
	s_add_i32 s6, s44, 0x83
	s_mul_hi_i32 s7, s6, 0x5600
	s_mulk_i32 s6, 0x5600
	v_mov_b32_dpp v144, v112 row_shr:1 row_mask:0xf bank_mask:0xf bound_ctrl:1
	v_mov_b32_dpp v145, v113 row_shr:1 row_mask:0xf bank_mask:0xf bound_ctrl:1
	v_mov_b32_dpp v142, v114 row_shr:1 row_mask:0xf bank_mask:0xf bound_ctrl:1
	v_mov_b32_dpp v143, v115 row_shr:1 row_mask:0xf bank_mask:0xf bound_ctrl:1
	v_mov_b32_dpp v150, v100 row_shr:1 row_mask:0xf bank_mask:0xf bound_ctrl:1
	v_mov_b32_dpp v152, v101 row_shr:1 row_mask:0xf bank_mask:0xf bound_ctrl:1
	v_mov_b32_dpp v151, v102 row_shr:1 row_mask:0xf bank_mask:0xf bound_ctrl:1
	v_mov_b32_dpp v153, v103 row_shr:1 row_mask:0xf bank_mask:0xf bound_ctrl:1
	s_and_saveexec_b64 s[44:45], s[42:43]
	s_cbranch_execz .LBB0_771
	s_lshl_b64 s[66:67], s[6:7], 1
	v_mul_f32_e32 v138, v114, v174
	v_mul_f32_e32 v139, v115, v175
	v_mul_f32_e32 v140, v112, v172
	v_mul_f32_e32 v141, v113, v173
	s_add_u32 s66, s56, s66
	v_fma_f32 v138, v102, v170, v138
	v_fma_f32 v139, v103, v171, v139
	v_fma_f32 v140, v100, v168, v140
	v_fma_f32 v141, v101, v169, v141
	s_addc_u32 s67, s57, s67
	v_cvt_pkrtz_f16_f32 v140, v140, v141
	v_cvt_pkrtz_f16_f32 v141, v138, v139
	v_lshl_add_u64 v[138:139], v[218:219], 1, s[66:67]
	flat_store_dwordx2 v[138:139], v[140:141]
	v_mul_f32_e32 v140, v114, v170
	v_mul_f32_e32 v141, v115, v171
	v_mul_f32_e32 v146, v112, v168
	v_mul_f32_e32 v147, v113, v169
	v_add_co_u32_e32 v138, vcc, 0x5000, v138
	v_cvt_pkrtz_f16_f32 v146, v146, v147
	v_cvt_pkrtz_f16_f32 v147, v140, v141
	v_addc_co_u32_e32 v139, vcc, 0, v139, vcc
	flat_store_dwordx2 v[138:139], v[146:147] offset:1536
; __device__ __forceinline__ u32x2 pack4(f32x4 v) { u32x2 r; r.x = cvt_pk_bf16(v[0], v[1]); r.y = cvt_pk_bf16(v[2], v[3]); return r; }
;     __device__ __forceinline__ void operator()(AccRef acc, const pg8::Unit& u, int wr, int wc, int fr, int fq) const {
;     ...
;                     f32x4 s3 = dpp4<0x111>(h3), s2 = dpp4<0x111>(h2);
;                     if (fr == 0) { s3 = zero; s2 = zero; }
;                     const f32x4 c0 = bb[bj] + w0[bj] * s2 + w1[bj] * s3 + w2[bj] * h0;
;                     const f32x4 c1 = bb[bj] + w0[bj] * s3 + w1[bj] * h0 + w2[bj] * h1;
;                     const f32x4 c2 = bb[bj] + w0[bj] * h0 + w1[bj] * h1 + w2[bj] * h2;
;                     const f32x4 c3 = bb[bj] + w0[bj] * h1 + w1[bj] * h2 + w2[bj] * h3;
;                     if (bj == 0) { cv[0] = c0; cv[1] = c1; cv[2] = c2; cv[3] = c3; } else { cg[0] = c0; cg[1] = c1; cg[2] = c2; cg[3] = c3; }
;                     if (has_next && fr == 15) {
;                         const size_t o1 = ((size_t)(1 * NSLAB + slab + 1) * 2) * NUP;
;                         *(u32x2*)((bf16_t*)BND + o1 + fc) = pack4(w0[bj] * h2 + w1[bj] * h3); *(u32x2*)((bf16_t*)BND + o1 + NUP + fc) = pack4(w0[bj] * h3);
.LBB0_771:
	s_or_b64 exec, exec, s[44:45]
	v_mov_b32_dpp v140, v104 row_shr:1 row_mask:0xf bank_mask:0xf bound_ctrl:1
	v_mov_b32_dpp v141, v105 row_shr:1 row_mask:0xf bank_mask:0xf bound_ctrl:1
	v_mov_b32_dpp v138, v106 row_shr:1 row_mask:0xf bank_mask:0xf bound_ctrl:1
	v_mov_b32_dpp v139, v107 row_shr:1 row_mask:0xf bank_mask:0xf bound_ctrl:1
	v_mov_b32_dpp v146, v108 row_shr:1 row_mask:0xf bank_mask:0xf bound_ctrl:1
	v_mov_b32_dpp v148, v109 row_shr:1 row_mask:0xf bank_mask:0xf bound_ctrl:1
	v_mov_b32_dpp v147, v110 row_shr:1 row_mask:0xf bank_mask:0xf bound_ctrl:1
	v_mov_b32_dpp v149, v111 row_shr:1 row_mask:0xf bank_mask:0xf bound_ctrl:1
	s_and_saveexec_b64 s[44:45], s[42:43]
	s_cbranch_execz .LBB0_773
	s_lshl_b64 s[66:67], s[6:7], 1
	v_mul_f32_e32 v154, v106, v186
	v_mul_f32_e32 v155, v107, v187
	v_mul_f32_e32 v156, v104, v184
	v_mul_f32_e32 v157, v105, v185
	s_add_u32 s66, s56, s66
	v_fma_f32 v154, v110, v182, v154
	v_fma_f32 v155, v111, v183, v155
	v_fma_f32 v156, v108, v180, v156
	v_fma_f32 v157, v109, v181, v157
	s_addc_u32 s67, s57, s67
	v_cvt_pkrtz_f16_f32 v156, v156, v157
	v_cvt_pkrtz_f16_f32 v157, v154, v155
	v_lshl_add_u64 v[154:155], v[220:221], 1, s[66:67]
	flat_store_dwordx2 v[154:155], v[156:157]
	v_mul_f32_e32 v156, v106, v182
	v_mul_f32_e32 v157, v107, v183
	v_mul_f32_e32 v158, v104, v180
	v_mul_f32_e32 v159, v105, v181
	v_add_co_u32_e32 v154, vcc, 0x5000, v154
	v_cvt_pkrtz_f16_f32 v158, v158, v159
	v_cvt_pkrtz_f16_f32 v159, v156, v157
	v_addc_co_u32_e32 v155, vcc, 0, v155, vcc
	flat_store_dwordx2 v[154:155], v[158:159] offset:1536
.LBB0_773:
	s_or_b64 exec, exec, s[44:45]
	v_mov_b32_e32 v155, v148
	v_mov_b32_e32 v154, v146
	v_mov_b32_e32 v148, v147
	v_fma_f32 v146, v182, v148, v194
	v_fma_f32 v147, v183, v149, v195
	v_fma_f32 v148, v180, v154, v192
	v_fma_f32 v149, v181, v155, v193
	v_mov_b32_e32 v155, v152
	v_mov_b32_e32 v154, v150
	v_mov_b32_e32 v152, v151
	v_fma_f32 v150, v170, v152, v178
	v_fma_f32 v151, v171, v153, v179
	v_fma_f32 v152, v168, v154, v176
	v_fma_f32 v153, v169, v155, v177
	s_cmp_lg_u32 s63, 0
	v_fma_f32 v148, v184, v140, v148
	v_fma_f32 v149, v185, v141, v149
	v_fma_f32 v146, v186, v138, v146
	v_fma_f32 v147, v187, v139, v147
	v_fma_f32 v152, v172, v144, v152
	v_fma_f32 v153, v173, v145, v153
	v_fma_f32 v150, v174, v142, v150
	v_fma_f32 v151, v175, v143, v151
	s_cselect_b64 s[44:45], -1, 0
	s_xor_b64 s[4:5], s[4:5], -1
	v_fma_f32 v146, v126, v190, v146
	v_fma_f32 v147, v127, v191, v147
	v_fma_f32 v148, v124, v188, v148
	v_fma_f32 v149, v125, v189, v149
	v_fma_f32 v150, v130, v166, v150
	v_fma_f32 v151, v131, v167, v151
	v_fma_f32 v152, v128, v164, v152
	v_fma_f32 v153, v129, v165, v153
	s_and_b64 s[4:5], s[4:5], s[44:45]
	s_mul_hi_i32 s63, s65, 0xac00
	s_mul_i32 s64, s65, 0xac00
	s_and_saveexec_b64 s[44:45], s[4:5]
	s_xor_b64 s[44:45], exec, s[44:45]
	s_cbranch_execz .LBB0_775
	s_add_u32 s66, s56, s64
	s_addc_u32 s67, s57, s63
	v_cvt_pkrtz_f16_f32 v152, v152, v153
	v_cvt_pkrtz_f16_f32 v153, v150, v151
	v_lshl_add_u64 v[150:151], v[218:219], 1, s[66:67]
	v_cvt_pkrtz_f16_f32 v148, v148, v149
	v_cvt_pkrtz_f16_f32 v149, v146, v147
	v_lshl_add_u64 v[146:147], v[220:221], 1, s[66:67]
	flat_store_dwordx2 v[150:151], v[152:153]
	flat_store_dwordx2 v[146:147], v[148:149]

;     __device__ __forceinline__ void operator()(AccRef acc, const pg8::Unit& u, int wr, int wc, int fr, int fq) const {
;     ...
;                     const f32x4 c1 = bb[bj] + w0[bj] * s3 + w1[bj] * h0 + w2[bj] * h1;
.LBB0_777:
	s_or_b64 exec, exec, s[44:45]
	v_fma_f32 v140, v180, v140, v192
	v_fma_f32 v141, v181, v141, v193
	v_fma_f32 v138, v182, v138, v194
	v_fma_f32 v139, v183, v139, v195
	v_fma_f32 v140, v124, v184, v140
	v_fma_f32 v141, v125, v185, v141
	v_fma_f32 v138, v126, v186, v138
	v_fma_f32 v139, v127, v187, v139
	v_fma_f32 v146, v116, v188, v140
	v_fma_f32 v147, v117, v189, v141
	v_fma_f32 v140, v170, v142, v178
	v_fma_f32 v141, v171, v143, v179
	v_fma_f32 v142, v168, v144, v176
	v_fma_f32 v143, v169, v145, v177
	v_fma_f32 v140, v130, v174, v140
	v_fma_f32 v141, v131, v175, v141
	v_fma_f32 v142, v128, v172, v142
	v_fma_f32 v143, v129, v173, v143
	v_fma_f32 v138, v118, v190, v138
	v_fma_f32 v139, v119, v191, v139
	v_fma_f32 v140, v122, v166, v140
	v_fma_f32 v141, v123, v167, v141
	v_fma_f32 v142, v120, v164, v142
	v_fma_f32 v143, v121, v165, v143
	s_and_saveexec_b64 s[44:45], s[4:5]
	s_xor_b64 s[44:45], exec, s[44:45]
	s_cbranch_execz .LBB0_779
	s_add_u32 s65, s56, s64
	s_addc_u32 s67, s57, s63
	s_add_u32 s66, s65, 0x5600
	s_addc_u32 s67, s67, 0
	v_cvt_pkrtz_f16_f32 v142, v142, v143
	v_cvt_pkrtz_f16_f32 v143, v140, v141
	v_lshl_add_u64 v[140:141], v[218:219], 1, s[66:67]
	flat_store_dwordx2 v[140:141], v[142:143]
	v_cvt_pkrtz_f16_f32 v140, v146, v147
	v_cvt_pkrtz_f16_f32 v141, v138, v139
	v_lshl_add_u64 v[138:139], v[220:221], 1, s[66:67]
	flat_store_dwordx2 v[138:139], v[140:141]

; __device__ __forceinline__ u32x2 pack4(f32x4 v) { u32x2 r; r.x = cvt_pk_bf16(v[0], v[1]); r.y = cvt_pk_bf16(v[2], v[3]); return r; }
; __device__ __forceinline__ float sigmoidf_(float x) { return __builtin_amdgcn_rcpf(1.0f + __expf(-x)); }
;     __device__ __forceinline__ void operator()(AccRef acc, const pg8::Unit& u, int wr, int wc, int fr, int fq) const {
;     ...
;                     const f32x4 c2 = bb[bj] + w0[bj] * h0 + w1[bj] * h1 + w2[bj] * h2;
;                     const f32x4 c3 = bb[bj] + w0[bj] * h1 + w1[bj] * h2 + w2[bj] * h3;
;                     if (bj == 0) { cv[0] = c0; cv[1] = c1; cv[2] = c2; cv[3] = c3; } else { cg[0] = c0; cg[1] = c1; cg[2] = c2; cg[3] = c3; }
;                     if (has_next && fr == 15) {
;                         const size_t o1 = ((size_t)(1 * NSLAB + slab + 1) * 2) * NUP;
;                         *(u32x2*)((bf16_t*)BND + o1 + fc) = pack4(w0[bj] * h2 + w1[bj] * h3); *(u32x2*)((bf16_t*)BND + o1 + NUP + fc) = pack4(w0[bj] * h3);
;                     }
;                 }
; #pragma unroll
;                 for (int m = 0; m < 4; ++m) {
;                     if (m < 2 && fr == 0 && !bstart) {
;                         const size_t o0 = ((size_t)(0 * NSLAB + slab) * 2 + m) * NUP;
;                         *(u32x2*)((bf16_t*)BND + o0 + fv) = pack4(cv[m]); *(u32x2*)((bf16_t*)BND + o0 + fg) = pack4(cg[m]);
;                     } else {
;                         f32x4 a;
; #pragma unroll
;                         for (int j = 0; j < 4; ++j) a[j] = cv[m][j] * cg[m][j] * sigmoidf_(cg[m][j]);
;                         *(u32x2*)(ACT + (size_t)(slab * 64 + 4 * fr + m) * DFF + fv) = pack4(a);
.LBB0_781:
	s_or_b64 exec, exec, s[44:45]
	v_fma_f32 v138, v118, v182, v194
	v_fma_f32 v139, v119, v183, v195
	v_fma_f32 v140, v116, v180, v192
	v_fma_f32 v141, v117, v181, v193
	v_fma_f32 v138, v110, v186, v138
	v_fma_f32 v139, v111, v187, v139
	v_fma_f32 v140, v108, v184, v140
	v_fma_f32 v141, v109, v185, v141
	v_fma_f32 v106, v106, v190, v138
	v_fma_f32 v107, v107, v191, v139
	v_fma_f32 v138, v104, v188, v140
	v_fma_f32 v139, v105, v189, v141
	v_fma_f32 v104, v126, v182, v194
	v_fma_f32 v105, v127, v183, v195
	v_fma_f32 v124, v124, v180, v192
	v_fma_f32 v125, v125, v181, v193
	v_fma_f32 v104, v118, v186, v104
	v_fma_f32 v105, v119, v187, v105
	v_fma_f32 v116, v116, v184, v124
	v_fma_f32 v117, v117, v185, v125
	v_fma_f32 v110, v110, v190, v104
	v_fma_f32 v111, v111, v191, v105
	v_fma_f32 v104, v122, v170, v178
	v_fma_f32 v105, v123, v171, v179
	v_fma_f32 v108, v108, v188, v116
	v_fma_f32 v109, v109, v189, v117
	v_fma_f32 v104, v102, v174, v104
	v_fma_f32 v105, v103, v175, v105
	v_fma_f32 v116, v120, v168, v176
	v_fma_f32 v117, v121, v169, v177
	v_fma_f32 v114, v114, v166, v104
	v_fma_f32 v115, v115, v167, v105
	v_fma_f32 v104, v130, v170, v178
	v_fma_f32 v105, v131, v171, v179
	v_fma_f32 v116, v100, v172, v116
	v_fma_f32 v117, v101, v173, v117
	v_fma_f32 v104, v122, v174, v104
	v_fma_f32 v105, v123, v175, v105
	v_fma_f32 v112, v112, v164, v116
	v_fma_f32 v113, v113, v165, v117
	v_fma_f32 v102, v102, v166, v104
	v_fma_f32 v103, v103, v167, v105
	v_mul_f32_e32 v104, 0xbfb8aa3b, v108
	v_exp_f32_e32 v118, v104
	v_fma_f32 v116, v128, v168, v176
	v_fma_f32 v117, v129, v169, v177
	v_mul_f32_e32 v102, v102, v110
	v_fma_f32 v116, v120, v172, v116
	v_fma_f32 v117, v121, v173, v117
	v_or_b32_e32 v104, 4, v218
	v_fma_f32 v100, v100, v164, v116
	v_fma_f32 v101, v101, v165, v117
	v_mul_f32_e32 v117, 0xbfb8aa3b, v109
	v_add_f32_e32 v116, 1.0, v118
	v_exp_f32_e32 v117, v117
	v_rcp_f32_e32 v116, v116
	v_mul_f32_e32 v100, v100, v108
	v_mul_f32_e32 v101, v101, v109
	v_add_f32_e32 v108, 1.0, v117
	v_mul_f32_e32 v109, 0xbfb8aa3b, v110
	v_mul_f32_e32 v100, v100, v116
	v_rcp_f32_e32 v108, v108
	v_exp_f32_e32 v109, v109
	v_mul_f32_e32 v116, 0xbfb8aa3b, v111
	v_exp_f32_e32 v116, v116
	v_mul_f32_e32 v101, v101, v108
	v_add_f32_e32 v108, 1.0, v109
	v_rcp_f32_e32 v108, v108
	v_add_f32_e32 v109, 1.0, v116
	v_rcp_f32_e32 v109, v109
	v_ashrrev_i32_e32 v105, 31, v104
	v_mul_f32_e32 v108, v102, v108
	v_mul_f32_e32 v102, v103, v111
	v_mul_f32_e32 v103, v102, v109
	v_cvt_pkrtz_f16_f32 v102, v100, v101
	v_cvt_pkrtz_f16_f32 v103, v108, v103
	v_or_b32_e32 v100, 2, v154
	v_mov_b64_e32 v[108:109], s[22:23]
	v_mul_f32_e32 v101, 0xbfb8aa3b, v138
	v_exp_f32_e32 v110, v101
	v_mad_i64_i32 v[100:101], s[44:45], v100, s33, v[108:109]
	v_lshl_add_u64 v[100:101], v[100:101], 0, v[136:137]
	flat_store_dwordx2 v[100:101], v[102:103]
	v_mul_f32_e32 v103, 0xbfb8aa3b, v139
	v_exp_f32_e32 v103, v103
	v_add_f32_e32 v102, 1.0, v110
	v_rcp_f32_e32 v102, v102
	v_mul_f32_e32 v111, 0xbfb8aa3b, v106
	v_add_f32_e32 v103, 1.0, v103
	v_mul_f32_e32 v110, v112, v138
	v_rcp_f32_e32 v103, v103
	v_exp_f32_e32 v111, v111
	v_mul_f32_e32 v112, 0xbfb8aa3b, v107
	v_exp_f32_e32 v112, v112
	v_mul_f32_e32 v102, v110, v102
	v_mul_f32_e32 v110, v113, v139
	v_mul_f32_e32 v103, v110, v103
	v_add_f32_e32 v110, 1.0, v111
	v_rcp_f32_e32 v110, v110
	v_add_f32_e32 v111, 1.0, v112
	v_rcp_f32_e32 v111, v111
	v_mul_f32_e32 v106, v114, v106
	v_mul_f32_e32 v110, v106, v110
	v_mul_f32_e32 v106, v115, v107
	v_mul_f32_e32 v107, v106, v111
	v_cvt_pkrtz_f16_f32 v106, v102, v103
	v_or_b32_e32 v102, 3, v154
	v_mad_i64_i32 v[102:103], s[44:45], v102, s33, v[108:109]
	v_cvt_pkrtz_f16_f32 v107, v110, v107
	v_lshl_add_u64 v[102:103], v[102:103], 0, v[136:137]
	flat_store_dwordx2 v[102:103], v[106:107]
	v_mov_b32_dpp v114, v44 row_shr:1 row_mask:0xf bank_mask:0xf bound_ctrl:1
	v_mov_b32_dpp v115, v45 row_shr:1 row_mask:0xf bank_mask:0xf bound_ctrl:1
	v_mov_b32_dpp v112, v46 row_shr:1 row_mask:0xf bank_mask:0xf bound_ctrl:1
	v_mov_b32_dpp v113, v47 row_shr:1 row_mask:0xf bank_mask:0xf bound_ctrl:1
	v_mov_b32_dpp v120, v36 row_shr:1 row_mask:0xf bank_mask:0xf bound_ctrl:1
	v_mov_b32_dpp v122, v37 row_shr:1 row_mask:0xf bank_mask:0xf bound_ctrl:1
	v_mov_b32_dpp v121, v38 row_shr:1 row_mask:0xf bank_mask:0xf bound_ctrl:1
	v_mov_b32_dpp v123, v39 row_shr:1 row_mask:0xf bank_mask:0xf bound_ctrl:1
	s_and_saveexec_b64 s[44:45], s[40:41]
	s_cbranch_execz .LBB0_783
	s_lshl_b64 s[66:67], s[38:39], 1
	v_mul_f32_e32 v106, v46, v70
	v_mul_f32_e32 v107, v47, v71
	v_mul_f32_e32 v108, v44, v68
	v_mul_f32_e32 v109, v45, v69
	s_add_u32 s66, s56, s66
	v_fma_f32 v106, v38, v78, v106
	v_fma_f32 v107, v39, v79, v107
	v_fma_f32 v108, v36, v76, v108
	v_fma_f32 v109, v37, v77, v109
	s_addc_u32 s67, s57, s67
	v_cvt_pkrtz_f16_f32 v108, v108, v109
	v_cvt_pkrtz_f16_f32 v109, v106, v107
	v_lshl_add_u64 v[106:107], v[218:219], 1, s[66:67]
	flat_store_dwordx2 v[106:107], v[108:109] offset:8
	v_mul_f32_e32 v106, v46, v78
	v_mul_f32_e32 v107, v47, v79
	v_mul_f32_e32 v108, v44, v76
	v_mul_f32_e32 v109, v45, v77
	s_nop 0
	v_cvt_pkrtz_f16_f32 v108, v108, v109
	v_cvt_pkrtz_f16_f32 v109, v106, v107
	v_lshl_add_u64 v[106:107], v[104:105], 1, s[66:67]
	v_add_co_u32_e32 v106, vcc, 0x5000, v106
	s_nop 1
	v_addc_co_u32_e32 v107, vcc, 0, v107, vcc
	flat_store_dwordx2 v[106:107], v[108:109] offset:1536
; __device__ __forceinline__ u32x2 pack4(f32x4 v) { u32x2 r; r.x = cvt_pk_bf16(v[0], v[1]); r.y = cvt_pk_bf16(v[2], v[3]); return r; }
;     __device__ __forceinline__ void operator()(AccRef acc, const pg8::Unit& u, int wr, int wc, int fr, int fq) const {
;     ...
;                     f32x4 s3 = dpp4<0x111>(h3), s2 = dpp4<0x111>(h2);
;                     if (fr == 0) { s3 = zero; s2 = zero; }
;                     const f32x4 c0 = bb[bj] + w0[bj] * s2 + w1[bj] * s3 + w2[bj] * h0;
;                     const f32x4 c1 = bb[bj] + w0[bj] * s3 + w1[bj] * h0 + w2[bj] * h1;
;                     const f32x4 c2 = bb[bj] + w0[bj] * h0 + w1[bj] * h1 + w2[bj] * h2;
;                     const f32x4 c3 = bb[bj] + w0[bj] * h1 + w1[bj] * h2 + w2[bj] * h3;
;                     if (bj == 0) { cv[0] = c0; cv[1] = c1; cv[2] = c2; cv[3] = c3; } else { cg[0] = c0; cg[1] = c1; cg[2] = c2; cg[3] = c3; }
;                     if (has_next && fr == 15) {
;                         const size_t o1 = ((size_t)(1 * NSLAB + slab + 1) * 2) * NUP;
;                         *(u32x2*)((bf16_t*)BND + o1 + fc) = pack4(w0[bj] * h2 + w1[bj] * h3); *(u32x2*)((bf16_t*)BND + o1 + NUP + fc) = pack4(w0[bj] * h3);
.LBB0_783:
	s_or_b64 exec, exec, s[44:45]
	v_add_u32_e32 v106, 0x1584, v218
	v_ashrrev_i32_e32 v107, 31, v106
	v_mov_b32_dpp v110, v52 row_shr:1 row_mask:0xf bank_mask:0xf bound_ctrl:1
	v_mov_b32_dpp v111, v53 row_shr:1 row_mask:0xf bank_mask:0xf bound_ctrl:1
	v_mov_b32_dpp v108, v54 row_shr:1 row_mask:0xf bank_mask:0xf bound_ctrl:1
	v_mov_b32_dpp v109, v55 row_shr:1 row_mask:0xf bank_mask:0xf bound_ctrl:1
	v_mov_b32_dpp v116, v40 row_shr:1 row_mask:0xf bank_mask:0xf bound_ctrl:1
	v_mov_b32_dpp v118, v41 row_shr:1 row_mask:0xf bank_mask:0xf bound_ctrl:1
	v_mov_b32_dpp v117, v42 row_shr:1 row_mask:0xf bank_mask:0xf bound_ctrl:1
	v_mov_b32_dpp v119, v43 row_shr:1 row_mask:0xf bank_mask:0xf bound_ctrl:1
	s_and_saveexec_b64 s[44:45], s[40:41]
	s_cbranch_execz .LBB0_785
	s_lshl_b64 s[38:39], s[38:39], 1
	v_mul_f32_e32 v124, v54, v94
	v_mul_f32_e32 v125, v55, v95
	v_mul_f32_e32 v126, v52, v92
	v_mul_f32_e32 v127, v53, v93
	s_add_u32 s38, s56, s38
	v_fma_f32 v124, v42, v90, v124
	v_fma_f32 v125, v43, v91, v125
	v_fma_f32 v126, v40, v88, v126
	v_fma_f32 v127, v41, v89, v127
	s_addc_u32 s39, s57, s39
	v_cvt_pkrtz_f16_f32 v126, v126, v127
	v_cvt_pkrtz_f16_f32 v127, v124, v125
	v_lshl_add_u64 v[124:125], v[106:107], 1, s[38:39]
	flat_store_dwordx2 v[124:125], v[126:127]
	v_mul_f32_e32 v126, v54, v90
	v_mul_f32_e32 v127, v55, v91
	v_mul_f32_e32 v128, v52, v88
	v_mul_f32_e32 v129, v53, v89
	v_add_co_u32_e32 v124, vcc, 0x5000, v124
	v_cvt_pkrtz_f16_f32 v128, v128, v129
	v_cvt_pkrtz_f16_f32 v129, v126, v127
	v_addc_co_u32_e32 v125, vcc, 0, v125, vcc
	flat_store_dwordx2 v[124:125], v[128:129] offset:1536
.LBB0_785:
	s_or_b64 exec, exec, s[44:45]
	v_mov_b32_e32 v125, v118
	v_mov_b32_e32 v124, v116
	v_mov_b32_e32 v118, v117
	v_fma_f32 v116, v90, v118, v98
	v_fma_f32 v117, v91, v119, v99
	v_fma_f32 v118, v88, v124, v96
	v_fma_f32 v119, v89, v125, v97
	v_mov_b32_e32 v125, v122
	v_mov_b32_e32 v124, v120
	v_mov_b32_e32 v122, v121
	v_fma_f32 v120, v78, v122, v82
	v_fma_f32 v121, v79, v123, v83
	v_fma_f32 v122, v76, v124, v80
	v_fma_f32 v123, v77, v125, v81
	v_fma_f32 v118, v92, v110, v118
	v_fma_f32 v119, v93, v111, v119
	v_fma_f32 v116, v94, v108, v116
	v_fma_f32 v117, v95, v109, v117
	v_fma_f32 v122, v68, v114, v122
	v_fma_f32 v123, v69, v115, v123
	v_fma_f32 v120, v70, v112, v120
	v_fma_f32 v121, v71, v113, v121
	v_fma_f32 v116, v62, v86, v116
	v_fma_f32 v117, v63, v87, v117
	v_fma_f32 v118, v60, v84, v118
	v_fma_f32 v119, v61, v85, v119
	v_fma_f32 v120, v66, v74, v120
	v_fma_f32 v121, v67, v75, v121
	v_fma_f32 v122, v64, v72, v122
	v_fma_f32 v123, v65, v73, v123
	s_and_saveexec_b64 s[38:39], s[36:37]
	s_xor_b64 s[38:39], exec, s[38:39]
	s_cbranch_execz .LBB0_787
	s_add_u32 s40, s56, s29
	s_addc_u32 s41, s57, s27
	v_cvt_pkrtz_f16_f32 v122, v122, v123
	v_cvt_pkrtz_f16_f32 v123, v120, v121
	v_lshl_add_u64 v[120:121], v[218:219], 1, s[40:41]
	v_cvt_pkrtz_f16_f32 v118, v118, v119
	v_cvt_pkrtz_f16_f32 v119, v116, v117
	v_lshl_add_u64 v[116:117], v[106:107], 1, s[40:41]
	flat_store_dwordx2 v[120:121], v[122:123] offset:8
	flat_store_dwordx2 v[116:117], v[118:119]

;     __device__ __forceinline__ void operator()(AccRef acc, const pg8::Unit& u, int wr, int wc, int fr, int fq) const {
;     ...
;                     const f32x4 c1 = bb[bj] + w0[bj] * s3 + w1[bj] * h0 + w2[bj] * h1;
.LBB0_789:
	s_or_b64 exec, exec, s[38:39]
	v_fma_f32 v110, v88, v110, v96
	v_fma_f32 v111, v89, v111, v97
	v_fma_f32 v108, v90, v108, v98
	v_fma_f32 v109, v91, v109, v99
	v_fma_f32 v110, v60, v92, v110
	v_fma_f32 v111, v61, v93, v111
	v_fma_f32 v108, v62, v94, v108
	v_fma_f32 v109, v63, v95, v109
	v_fma_f32 v116, v56, v84, v110
	v_fma_f32 v117, v57, v85, v111
	v_fma_f32 v110, v78, v112, v82
	v_fma_f32 v111, v79, v113, v83
	v_fma_f32 v112, v76, v114, v80
	v_fma_f32 v113, v77, v115, v81
	v_fma_f32 v110, v66, v70, v110
	v_fma_f32 v111, v67, v71, v111
	v_fma_f32 v112, v64, v68, v112
	v_fma_f32 v113, v65, v69, v113
	v_fma_f32 v108, v58, v86, v108
	v_fma_f32 v109, v59, v87, v109
	v_fma_f32 v110, v50, v74, v110
	v_fma_f32 v111, v51, v75, v111
	v_fma_f32 v112, v48, v72, v112
	v_fma_f32 v113, v49, v73, v113
	s_and_saveexec_b64 s[38:39], s[36:37]
	s_xor_b64 s[36:37], exec, s[38:39]
	s_cbranch_execz .LBB0_791
	s_add_u32 s29, s56, s29
	s_addc_u32 s27, s57, s27
	s_add_u32 s38, s29, 0x5600
	s_addc_u32 s39, s27, 0
	v_cvt_pkrtz_f16_f32 v112, v112, v113
	v_cvt_pkrtz_f16_f32 v113, v110, v111
	v_lshl_add_u64 v[110:111], v[104:105], 1, s[38:39]
	flat_store_dwordx2 v[110:111], v[112:113]
	v_cvt_pkrtz_f16_f32 v110, v116, v117
	v_cvt_pkrtz_f16_f32 v111, v108, v109
	v_lshl_add_u64 v[108:109], v[106:107], 1, s[38:39]
	flat_store_dwordx2 v[108:109], v[110:111]

; __device__ __forceinline__ u32x2 pack4(f32x4 v) { u32x2 r; r.x = cvt_pk_bf16(v[0], v[1]); r.y = cvt_pk_bf16(v[2], v[3]); return r; }
; __device__ __forceinline__ float sigmoidf_(float x) { return __builtin_amdgcn_rcpf(1.0f + __expf(-x)); }
;     __device__ __forceinline__ void operator()(AccRef acc, const pg8::Unit& u, int wr, int wc, int fr, int fq) const {
;     ...
;                     f32x4 s3 = dpp4<0x111>(h3), s2 = dpp4<0x111>(h2);
;                     if (fr == 0) { s3 = zero; s2 = zero; }
;                     const f32x4 c0 = bb[bj] + w0[bj] * s2 + w1[bj] * s3 + w2[bj] * h0;
;                     const f32x4 c1 = bb[bj] + w0[bj] * s3 + w1[bj] * h0 + w2[bj] * h1;
;                     const f32x4 c2 = bb[bj] + w0[bj] * h0 + w1[bj] * h1 + w2[bj] * h2;
;                     const f32x4 c3 = bb[bj] + w0[bj] * h1 + w1[bj] * h2 + w2[bj] * h3;
;                     if (bj == 0) { cv[0] = c0; cv[1] = c1; cv[2] = c2; cv[3] = c3; } else { cg[0] = c0; cg[1] = c1; cg[2] = c2; cg[3] = c3; }
;                     if (has_next && fr == 15) {
;                         const size_t o1 = ((size_t)(1 * NSLAB + slab + 1) * 2) * NUP;
;                         *(u32x2*)((bf16_t*)BND + o1 + fc) = pack4(w0[bj] * h2 + w1[bj] * h3); *(u32x2*)((bf16_t*)BND + o1 + NUP + fc) = pack4(w0[bj] * h3);
;                     }
;                 }
; #pragma unroll
;                 for (int m = 0; m < 4; ++m) {
;                     if (m < 2 && fr == 0 && !bstart) {
;                         const size_t o0 = ((size_t)(0 * NSLAB + slab) * 2 + m) * NUP;
;                         *(u32x2*)((bf16_t*)BND + o0 + fv) = pack4(cv[m]); *(u32x2*)((bf16_t*)BND + o0 + fg) = pack4(cg[m]);
;                     } else {
;                         f32x4 a;
; #pragma unroll
;                         for (int j = 0; j < 4; ++j) a[j] = cv[m][j] * cg[m][j] * sigmoidf_(cg[m][j]);
;                         *(u32x2*)(ACT + (size_t)(slab * 64 + 4 * fr + m) * DFF + fv) = pack4(a);
.LBB0_793:
	s_or_b64 exec, exec, s[36:37]
	v_fma_f32 v60, v60, v88, v96
	v_fma_f32 v61, v61, v89, v97
	v_fma_f32 v110, v56, v88, v96
	v_fma_f32 v111, v57, v89, v97
	v_fma_f32 v56, v56, v92, v60
	v_fma_f32 v57, v57, v93, v61
	v_fma_f32 v110, v40, v92, v110
	v_fma_f32 v111, v41, v93, v111
	v_fma_f32 v40, v40, v84, v56
	v_fma_f32 v41, v41, v85, v57
	v_fma_f32 v56, v50, v78, v82
	v_fma_f32 v57, v51, v79, v83
	v_fma_f32 v62, v62, v90, v98
	v_fma_f32 v63, v63, v91, v99
	v_fma_f32 v56, v38, v70, v56
	v_fma_f32 v57, v39, v71, v57
	v_fma_f32 v108, v58, v90, v98
	v_fma_f32 v109, v59, v91, v99
	v_fma_f32 v46, v46, v74, v56
	v_fma_f32 v47, v47, v75, v57
	v_fma_f32 v56, v66, v78, v82
	v_fma_f32 v57, v67, v79, v83
	v_fma_f32 v58, v58, v94, v62
	v_fma_f32 v59, v59, v95, v63
	v_fma_f32 v50, v50, v70, v56
	v_fma_f32 v51, v51, v71, v57
	v_mul_f32_e32 v56, 0xbfb8aa3b, v40
	v_fma_f32 v108, v42, v94, v108
	v_fma_f32 v109, v43, v95, v109
	v_fma_f32 v42, v42, v86, v58
	v_fma_f32 v43, v43, v87, v59
	v_fma_f32 v58, v48, v76, v80
	v_fma_f32 v59, v49, v77, v81
	v_exp_f32_e32 v56, v56
	v_fma_f32 v58, v36, v68, v58
	v_fma_f32 v59, v37, v69, v59
	v_fma_f32 v38, v38, v74, v50
	v_fma_f32 v39, v39, v75, v51
	v_fma_f32 v44, v44, v72, v58
	v_fma_f32 v45, v45, v73, v59
	v_fma_f32 v58, v64, v76, v80
	v_fma_f32 v59, v65, v77, v81
	v_mul_f32_e32 v38, v38, v42
	v_fma_f32 v48, v48, v68, v58
	v_fma_f32 v49, v49, v69, v59
	v_mul_f32_e32 v39, v39, v43
	v_fma_f32 v36, v36, v72, v48
	v_fma_f32 v37, v37, v73, v49
	v_add_f32_e32 v48, 1.0, v56
	v_mul_f32_e32 v49, 0xbfb8aa3b, v41
	v_rcp_f32_e32 v48, v48
	v_exp_f32_e32 v49, v49
	v_mul_f32_e32 v36, v36, v40
	v_mul_f32_e32 v37, v37, v41
	v_mul_f32_e32 v36, v36, v48
	v_add_f32_e32 v40, 1.0, v49
	v_mul_f32_e32 v41, 0xbfb8aa3b, v42
	v_mul_f32_e32 v48, 0xbfb8aa3b, v43
	v_rcp_f32_e32 v40, v40
	v_exp_f32_e32 v41, v41
	v_exp_f32_e32 v48, v48
	v_fma_f32 v52, v52, v84, v110
	v_fma_f32 v53, v53, v85, v111
	v_mul_f32_e32 v37, v37, v40
	v_add_f32_e32 v40, 1.0, v41
	v_add_f32_e32 v41, 1.0, v48
	v_rcp_f32_e32 v40, v40
	v_rcp_f32_e32 v41, v41
	v_cvt_pkrtz_f16_f32 v36, v36, v37
	v_fma_f32 v54, v54, v86, v108
	v_fma_f32 v55, v55, v87, v109
	v_mul_f32_e32 v38, v38, v40
	v_mul_f32_e32 v39, v39, v41
	v_mul_f32_e32 v40, 0xbfb8aa3b, v52
	v_cvt_pkrtz_f16_f32 v37, v38, v39
	v_exp_f32_e32 v40, v40
	flat_store_dwordx2 v[132:133], v[36:37] offset:8
	v_mul_f32_e32 v37, 0xbfb8aa3b, v53
	v_exp_f32_e32 v37, v37
	v_add_f32_e32 v36, 1.0, v40
	v_rcp_f32_e32 v36, v36
	v_mul_f32_e32 v39, 0xbfb8aa3b, v54
	v_add_f32_e32 v37, 1.0, v37
	v_rcp_f32_e32 v37, v37
	v_exp_f32_e32 v39, v39
	v_mul_f32_e32 v40, 0xbfb8aa3b, v55
	v_exp_f32_e32 v40, v40
	v_mul_f32_e32 v38, v44, v52
	v_mul_f32_e32 v36, v38, v36
	v_mul_f32_e32 v38, v45, v53
	v_mul_f32_e32 v37, v38, v37
	v_add_f32_e32 v38, 1.0, v39
	v_rcp_f32_e32 v38, v38
	v_add_f32_e32 v39, 1.0, v40
	v_rcp_f32_e32 v39, v39
	v_mul_f32_e32 v40, v46, v54
	v_mul_f32_e32 v38, v40, v38
	v_mul_f32_e32 v40, v47, v55
	v_mul_f32_e32 v39, v40, v39
	v_cvt_pkrtz_f16_f32 v36, v36, v37
	v_cvt_pkrtz_f16_f32 v37, v38, v39
	flat_store_dwordx2 v[134:135], v[36:37] offset:8
	v_mov_b32_dpp v42, v4 row_shr:1 row_mask:0xf bank_mask:0xf bound_ctrl:1
	v_mov_b32_dpp v43, v5 row_shr:1 row_mask:0xf bank_mask:0xf bound_ctrl:1
	v_mov_b32_dpp v40, v6 row_shr:1 row_mask:0xf bank_mask:0xf bound_ctrl:1
	v_mov_b32_dpp v41, v7 row_shr:1 row_mask:0xf bank_mask:0xf bound_ctrl:1
	v_mov_b32_dpp v48, v8 row_shr:1 row_mask:0xf bank_mask:0xf bound_ctrl:1
	v_mov_b32_dpp v50, v9 row_shr:1 row_mask:0xf bank_mask:0xf bound_ctrl:1
	v_mov_b32_dpp v49, v10 row_shr:1 row_mask:0xf bank_mask:0xf bound_ctrl:1
	v_mov_b32_dpp v51, v11 row_shr:1 row_mask:0xf bank_mask:0xf bound_ctrl:1
	s_and_saveexec_b64 s[36:37], s[42:43]
	s_cbranch_execz .LBB0_795
	s_lshl_b64 s[38:39], s[6:7], 1
	v_mul_f32_e32 v36, v6, v70
	v_mul_f32_e32 v37, v7, v71
	v_mul_f32_e32 v38, v4, v68
	v_mul_f32_e32 v39, v5, v69
	s_add_u32 s38, s56, s38
	v_fma_f32 v36, v10, v78, v36
	v_fma_f32 v37, v11, v79, v37
	v_fma_f32 v38, v8, v76, v38
	v_fma_f32 v39, v9, v77, v39
	s_addc_u32 s39, s57, s39
	v_cvt_pkrtz_f16_f32 v38, v38, v39
	v_cvt_pkrtz_f16_f32 v39, v36, v37
	v_lshl_add_u64 v[36:37], v[218:219], 1, s[38:39]
	flat_store_dwordx2 v[36:37], v[38:39] offset:8
	v_mul_f32_e32 v36, v6, v78
	v_mul_f32_e32 v37, v7, v79
	v_mul_f32_e32 v38, v4, v76
	v_mul_f32_e32 v39, v5, v77
	s_nop 0
	v_cvt_pkrtz_f16_f32 v38, v38, v39
	v_cvt_pkrtz_f16_f32 v39, v36, v37
	v_lshl_add_u64 v[36:37], v[104:105], 1, s[38:39]
	v_add_co_u32_e32 v36, vcc, 0x5000, v36
	s_nop 1
	v_addc_co_u32_e32 v37, vcc, 0, v37, vcc
	flat_store_dwordx2 v[36:37], v[38:39] offset:1536
; __device__ __forceinline__ u32x2 pack4(f32x4 v) { u32x2 r; r.x = cvt_pk_bf16(v[0], v[1]); r.y = cvt_pk_bf16(v[2], v[3]); return r; }
;     __device__ __forceinline__ void operator()(AccRef acc, const pg8::Unit& u, int wr, int wc, int fr, int fq) const {
;     ...
;                     const f32x4 h0 = acc[ai][bj][0][n], h1 = acc[ai][bj][1][n], h2 = acc[ai][bj][2][n], h3 = acc[ai][bj][3][n];
;                     f32x4 s3 = dpp4<0x111>(h3), s2 = dpp4<0x111>(h2);
;                     if (fr == 0) { s3 = zero; s2 = zero; }
;                     const f32x4 c0 = bb[bj] + w0[bj] * s2 + w1[bj] * s3 + w2[bj] * h0;
;                     const f32x4 c1 = bb[bj] + w0[bj] * s3 + w1[bj] * h0 + w2[bj] * h1;
;                     const f32x4 c2 = bb[bj] + w0[bj] * h0 + w1[bj] * h1 + w2[bj] * h2;
;                     const f32x4 c3 = bb[bj] + w0[bj] * h1 + w1[bj] * h2 + w2[bj] * h3;
;                     if (bj == 0) { cv[0] = c0; cv[1] = c1; cv[2] = c2; cv[3] = c3; } else { cg[0] = c0; cg[1] = c1; cg[2] = c2; cg[3] = c3; }
;                     if (has_next && fr == 15) {
;                         const size_t o1 = ((size_t)(1 * NSLAB + slab + 1) * 2) * NUP;
;                         *(u32x2*)((bf16_t*)BND + o1 + fc) = pack4(w0[bj] * h2 + w1[bj] * h3); *(u32x2*)((bf16_t*)BND + o1 + NUP + fc) = pack4(w0[bj] * h3);
;                     }
;                 }
; #pragma unroll
;                 for (int m = 0; m < 4; ++m) {
;                     if (m < 2 && fr == 0 && !bstart) {
;                         const size_t o0 = ((size_t)(0 * NSLAB + slab) * 2 + m) * NUP;
;                         *(u32x2*)((bf16_t*)BND + o0 + fv) = pack4(cv[m]); *(u32x2*)((bf16_t*)BND + o0 + fg) = pack4(cg[m]);
.LBB0_795:
	s_or_b64 exec, exec, s[36:37]
	v_mov_b32_dpp v38, v12 row_shr:1 row_mask:0xf bank_mask:0xf bound_ctrl:1
	v_mov_b32_dpp v39, v13 row_shr:1 row_mask:0xf bank_mask:0xf bound_ctrl:1
	v_mov_b32_dpp v36, v14 row_shr:1 row_mask:0xf bank_mask:0xf bound_ctrl:1
	v_mov_b32_dpp v37, v15 row_shr:1 row_mask:0xf bank_mask:0xf bound_ctrl:1
	v_mov_b32_dpp v44, v16 row_shr:1 row_mask:0xf bank_mask:0xf bound_ctrl:1
	v_mov_b32_dpp v46, v17 row_shr:1 row_mask:0xf bank_mask:0xf bound_ctrl:1
	v_mov_b32_dpp v45, v18 row_shr:1 row_mask:0xf bank_mask:0xf bound_ctrl:1
	v_mov_b32_dpp v47, v19 row_shr:1 row_mask:0xf bank_mask:0xf bound_ctrl:1
	s_and_saveexec_b64 s[36:37], s[42:43]
	s_cbranch_execz .LBB0_797
	s_lshl_b64 s[6:7], s[6:7], 1
	v_mul_f32_e32 v52, v14, v94
	v_mul_f32_e32 v53, v15, v95
	v_mul_f32_e32 v54, v12, v92
	v_mul_f32_e32 v55, v13, v93
	s_add_u32 s6, s56, s6
	v_fma_f32 v52, v18, v90, v52
	v_fma_f32 v53, v19, v91, v53
	v_fma_f32 v54, v16, v88, v54
	v_fma_f32 v55, v17, v89, v55
	s_addc_u32 s7, s57, s7
	v_cvt_pkrtz_f16_f32 v54, v54, v55
	v_cvt_pkrtz_f16_f32 v55, v52, v53
	v_lshl_add_u64 v[52:53], v[106:107], 1, s[6:7]
	flat_store_dwordx2 v[52:53], v[54:55]
	v_mul_f32_e32 v54, v14, v90
	v_mul_f32_e32 v55, v15, v91
	v_mul_f32_e32 v56, v12, v88
	v_mul_f32_e32 v57, v13, v89
	v_add_co_u32_e32 v52, vcc, 0x5000, v52
	v_cvt_pkrtz_f16_f32 v56, v56, v57
	v_cvt_pkrtz_f16_f32 v57, v54, v55
	v_addc_co_u32_e32 v53, vcc, 0, v53, vcc
	flat_store_dwordx2 v[52:53], v[56:57] offset:1536
.LBB0_797:
	s_or_b64 exec, exec, s[36:37]
	v_mov_b32_e32 v53, v46
	v_mov_b32_e32 v52, v44
	v_mov_b32_e32 v46, v45
	v_fma_f32 v44, v90, v46, v98
	v_fma_f32 v45, v91, v47, v99
	v_fma_f32 v46, v88, v52, v96
	v_fma_f32 v47, v89, v53, v97
	v_mov_b32_e32 v53, v50
	v_mov_b32_e32 v52, v48
	v_mov_b32_e32 v50, v49
	v_fma_f32 v48, v78, v50, v82
	v_fma_f32 v49, v79, v51, v83
	v_fma_f32 v50, v76, v52, v80
	v_fma_f32 v51, v77, v53, v81
	v_fma_f32 v46, v92, v38, v46
	v_fma_f32 v47, v93, v39, v47
	v_fma_f32 v44, v94, v36, v44
	v_fma_f32 v45, v95, v37, v45
	v_fma_f32 v50, v68, v42, v50
	v_fma_f32 v51, v69, v43, v51
	v_fma_f32 v48, v70, v40, v48
	v_fma_f32 v49, v71, v41, v49
	v_fma_f32 v44, v30, v86, v44
	v_fma_f32 v45, v31, v87, v45
	v_fma_f32 v46, v28, v84, v46
	v_fma_f32 v47, v29, v85, v47
	v_fma_f32 v48, v34, v74, v48
	v_fma_f32 v49, v35, v75, v49
	v_fma_f32 v50, v32, v72, v50
	v_fma_f32 v51, v33, v73, v51
	s_and_saveexec_b64 s[2:3], s[4:5]
	s_xor_b64 s[2:3], exec, s[2:3]
	s_cbranch_execz .LBB0_799
	s_add_u32 s6, s56, s64
	s_addc_u32 s7, s57, s63
	v_cvt_pkrtz_f16_f32 v50, v50, v51
	v_cvt_pkrtz_f16_f32 v51, v48, v49
	v_lshl_add_u64 v[48:49], v[218:219], 1, s[6:7]
	v_cvt_pkrtz_f16_f32 v46, v46, v47
	v_cvt_pkrtz_f16_f32 v47, v44, v45
	v_lshl_add_u64 v[44:45], v[106:107], 1, s[6:7]
	flat_store_dwordx2 v[48:49], v[50:51] offset:8
	flat_store_dwordx2 v[44:45], v[46:47]

; __device__ __forceinline__ u32x2 pack4(f32x4 v) { u32x2 r; r.x = cvt_pk_bf16(v[0], v[1]); r.y = cvt_pk_bf16(v[2], v[3]); return r; }
;     __device__ __forceinline__ void operator()(AccRef acc, const pg8::Unit& u, int wr, int wc, int fr, int fq) const {
;     ...
;                     const f32x4 c0 = bb[bj] + w0[bj] * s2 + w1[bj] * s3 + w2[bj] * h0;
;                     const f32x4 c1 = bb[bj] + w0[bj] * s3 + w1[bj] * h0 + w2[bj] * h1;
;                     const f32x4 c2 = bb[bj] + w0[bj] * h0 + w1[bj] * h1 + w2[bj] * h2;
;                     const f32x4 c3 = bb[bj] + w0[bj] * h1 + w1[bj] * h2 + w2[bj] * h3;
;                     if (bj == 0) { cv[0] = c0; cv[1] = c1; cv[2] = c2; cv[3] = c3; } else { cg[0] = c0; cg[1] = c1; cg[2] = c2; cg[3] = c3; }
;                     if (has_next && fr == 15) {
;                         const size_t o1 = ((size_t)(1 * NSLAB + slab + 1) * 2) * NUP;
;                         *(u32x2*)((bf16_t*)BND + o1 + fc) = pack4(w0[bj] * h2 + w1[bj] * h3); *(u32x2*)((bf16_t*)BND + o1 + NUP + fc) = pack4(w0[bj] * h3);
;                     }
;                 }
; #pragma unroll
;                 for (int m = 0; m < 4; ++m) {
;                     if (m < 2 && fr == 0 && !bstart) {
;                         const size_t o0 = ((size_t)(0 * NSLAB + slab) * 2 + m) * NUP;
;                         *(u32x2*)((bf16_t*)BND + o0 + fv) = pack4(cv[m]); *(u32x2*)((bf16_t*)BND + o0 + fg) = pack4(cg[m]);
.LBB0_801:
	s_or_b64 exec, exec, s[2:3]
	v_fma_f32 v38, v88, v38, v96
	v_fma_f32 v39, v89, v39, v97
	v_fma_f32 v36, v90, v36, v98
	v_fma_f32 v37, v91, v37, v99
	v_fma_f32 v38, v28, v92, v38
	v_fma_f32 v39, v29, v93, v39
	v_fma_f32 v36, v30, v94, v36
	v_fma_f32 v37, v31, v95, v37
	v_fma_f32 v44, v20, v84, v38
	v_fma_f32 v45, v21, v85, v39
	v_fma_f32 v38, v78, v40, v82
	v_fma_f32 v39, v79, v41, v83
	v_fma_f32 v40, v76, v42, v80
	v_fma_f32 v41, v77, v43, v81
	v_fma_f32 v38, v34, v70, v38
	v_fma_f32 v39, v35, v71, v39
	v_fma_f32 v40, v32, v68, v40
	v_fma_f32 v41, v33, v69, v41
	v_fma_f32 v36, v22, v86, v36
	v_fma_f32 v37, v23, v87, v37
	v_fma_f32 v38, v26, v74, v38
	v_fma_f32 v39, v27, v75, v39
	v_fma_f32 v40, v24, v72, v40
	v_fma_f32 v41, v25, v73, v41
	s_and_saveexec_b64 s[2:3], s[4:5]
	s_xor_b64 s[2:3], exec, s[2:3]
	s_cbranch_execz .LBB0_803
	s_add_u32 s4, s56, s64
	s_addc_u32 s5, s57, s63
	s_add_u32 s4, s4, 0x5600
	s_addc_u32 s5, s5, 0
	v_cvt_pkrtz_f16_f32 v40, v40, v41
	v_cvt_pkrtz_f16_f32 v41, v38, v39
	v_lshl_add_u64 v[38:39], v[104:105], 1, s[4:5]
	flat_store_dwordx2 v[38:39], v[40:41]
	v_cvt_pkrtz_f16_f32 v38, v44, v45
	v_cvt_pkrtz_f16_f32 v39, v36, v37
	v_lshl_add_u64 v[36:37], v[106:107], 1, s[4:5]
	flat_store_dwordx2 v[36:37], v[38:39]

; __device__ __forceinline__ u32x2 pack4(f32x4 v) { u32x2 r; r.x = cvt_pk_bf16(v[0], v[1]); r.y = cvt_pk_bf16(v[2], v[3]); return r; }
; __device__ __forceinline__ float sigmoidf_(float x) { return __builtin_amdgcn_rcpf(1.0f + __expf(-x)); }
;     __device__ __forceinline__ void operator()(AccRef acc, const pg8::Unit& u, int wr, int wc, int fr, int fq) const {
;     ...
;                     const f32x4 c0 = bb[bj] + w0[bj] * s2 + w1[bj] * s3 + w2[bj] * h0;
;                     const f32x4 c1 = bb[bj] + w0[bj] * s3 + w1[bj] * h0 + w2[bj] * h1;
;                     const f32x4 c2 = bb[bj] + w0[bj] * h0 + w1[bj] * h1 + w2[bj] * h2;
;                     const f32x4 c3 = bb[bj] + w0[bj] * h1 + w1[bj] * h2 + w2[bj] * h3;
;                     if (bj == 0) { cv[0] = c0; cv[1] = c1; cv[2] = c2; cv[3] = c3; } else { cg[0] = c0; cg[1] = c1; cg[2] = c2; cg[3] = c3; }
;                     if (has_next && fr == 15) {
;                         const size_t o1 = ((size_t)(1 * NSLAB + slab + 1) * 2) * NUP;
;                         *(u32x2*)((bf16_t*)BND + o1 + fc) = pack4(w0[bj] * h2 + w1[bj] * h3); *(u32x2*)((bf16_t*)BND + o1 + NUP + fc) = pack4(w0[bj] * h3);
;                     }
;                 }
; #pragma unroll
;                 for (int m = 0; m < 4; ++m) {
;                     if (m < 2 && fr == 0 && !bstart) {
;                         const size_t o0 = ((size_t)(0 * NSLAB + slab) * 2 + m) * NUP;
;                         *(u32x2*)((bf16_t*)BND + o0 + fv) = pack4(cv[m]); *(u32x2*)((bf16_t*)BND + o0 + fg) = pack4(cg[m]);
;                     } else {
;                         f32x4 a;
; #pragma unroll
;                         for (int j = 0; j < 4; ++j) a[j] = cv[m][j] * cg[m][j] * sigmoidf_(cg[m][j]);
;                         *(u32x2*)(ACT + (size_t)(slab * 64 + 4 * fr + m) * DFF + fv) = pack4(a);
;                     }
.LBB0_805:
	s_or_b64 exec, exec, s[2:3]
	v_fma_f32 v30, v30, v90, v98
	v_fma_f32 v31, v31, v91, v99
	v_fma_f32 v28, v28, v88, v96
	v_fma_f32 v29, v29, v89, v97
	v_fma_f32 v30, v22, v94, v30
	v_fma_f32 v31, v23, v95, v31
	v_fma_f32 v28, v20, v92, v28
	v_fma_f32 v29, v21, v93, v29
	v_fma_f32 v22, v22, v90, v98
	v_fma_f32 v23, v23, v91, v99
	v_fma_f32 v20, v20, v88, v96
	v_fma_f32 v21, v21, v89, v97
	v_fma_f32 v30, v18, v86, v30
	v_fma_f32 v31, v19, v87, v31
	v_fma_f32 v28, v16, v84, v28
	v_fma_f32 v29, v17, v85, v29
	v_fma_f32 v18, v18, v94, v22
	v_fma_f32 v19, v19, v95, v23
	v_fma_f32 v16, v16, v92, v20
	v_fma_f32 v17, v17, v93, v21
	v_fma_f32 v14, v14, v86, v18
	v_fma_f32 v15, v15, v87, v19
	v_fma_f32 v12, v12, v84, v16
	v_fma_f32 v13, v13, v85, v17
	v_fma_f32 v16, v34, v78, v82
	v_fma_f32 v17, v35, v79, v83
	v_fma_f32 v18, v32, v76, v80
	v_fma_f32 v19, v33, v77, v81
	v_fma_f32 v16, v26, v70, v16
	v_fma_f32 v17, v27, v71, v17
	v_fma_f32 v18, v24, v68, v18
	v_fma_f32 v19, v25, v69, v19
	v_fma_f32 v20, v26, v78, v82
	v_fma_f32 v21, v27, v79, v83
	v_fma_f32 v22, v24, v76, v80
	v_fma_f32 v23, v25, v77, v81
	v_fma_f32 v16, v10, v74, v16
	v_fma_f32 v17, v11, v75, v17
	v_fma_f32 v18, v8, v72, v18
	v_fma_f32 v19, v9, v73, v19
	v_fma_f32 v10, v10, v70, v20
	v_fma_f32 v11, v11, v71, v21
	v_mul_f32_e32 v20, 0xbfb8aa3b, v28
	v_fma_f32 v8, v8, v68, v22
	v_fma_f32 v9, v9, v69, v23
	v_exp_f32_e32 v20, v20
	v_fma_f32 v4, v4, v72, v8
	v_fma_f32 v5, v5, v73, v9
	v_mul_f32_e32 v9, 0xbfb8aa3b, v29
	v_exp_f32_e32 v9, v9
	v_add_f32_e32 v8, 1.0, v20
	v_fma_f32 v6, v6, v74, v10
	v_fma_f32 v7, v7, v75, v11
	v_rcp_f32_e32 v8, v8
	v_add_f32_e32 v9, 1.0, v9
	v_mul_f32_e32 v11, 0xbfb8aa3b, v30
	v_mul_f32_e32 v10, v18, v28
	v_rcp_f32_e32 v9, v9
	v_exp_f32_e32 v11, v11
	v_mul_f32_e32 v18, 0xbfb8aa3b, v31
	v_exp_f32_e32 v18, v18
	v_mul_f32_e32 v8, v10, v8
	v_mul_f32_e32 v10, v19, v29
	v_mul_f32_e32 v9, v10, v9
	v_add_f32_e32 v10, 1.0, v11
	v_rcp_f32_e32 v10, v10
	v_add_f32_e32 v11, 1.0, v18
	v_rcp_f32_e32 v11, v11
	v_mul_f32_e32 v16, v16, v30
	v_mul_f32_e32 v10, v16, v10
	v_mul_f32_e32 v16, v17, v31
	v_mul_f32_e32 v11, v16, v11
	v_mul_f32_e32 v16, 0xbfb8aa3b, v12
	v_exp_f32_e32 v16, v16
	v_cvt_pkrtz_f16_f32 v8, v8, v9
	v_cvt_pkrtz_f16_f32 v9, v10, v11
	flat_store_dwordx2 v[100:101], v[8:9] offset:8
	v_add_f32_e32 v8, 1.0, v16
	v_mul_f32_e32 v9, 0xbfb8aa3b, v13
	v_rcp_f32_e32 v8, v8
	v_exp_f32_e32 v9, v9
	v_mul_f32_e32 v4, v4, v12
	v_mul_f32_e32 v10, 0xbfb8aa3b, v15
	v_mul_f32_e32 v4, v4, v8
	v_add_f32_e32 v8, 1.0, v9
	v_mul_f32_e32 v9, 0xbfb8aa3b, v14
	v_rcp_f32_e32 v8, v8
	v_exp_f32_e32 v9, v9
	v_exp_f32_e32 v10, v10
	v_mul_f32_e32 v5, v5, v13
	v_mul_f32_e32 v5, v5, v8
	v_add_f32_e32 v8, 1.0, v9
	v_add_f32_e32 v9, 1.0, v10
	v_rcp_f32_e32 v8, v8
	v_rcp_f32_e32 v9, v9
	v_mul_f32_e32 v6, v6, v14
	v_mul_f32_e32 v7, v7, v15
	v_mul_f32_e32 v6, v6, v8
	v_mul_f32_e32 v7, v7, v9
	v_cvt_pkrtz_f16_f32 v4, v4, v5
	v_cvt_pkrtz_f16_f32 v5, v6, v7
	flat_store_dwordx2 v[102:103], v[4:5] offset:8
	s_andn2_b64 vcc, exec, s[0:1]
	s_mov_b64 s[0:1], -1
	s_cbranch_vccnz .LBB0_750
	s_andn2_b64 vcc, exec, s[8:9]
	s_cbranch_vccnz .LBB0_749
	s_barrier
	s_branch .LBB0_749
